# P3: one static s_setprio 1 for waves 4-7 for the whole attention phase
# baseline (speedup 1.0000x reference)
.LBB0_300:
	s_or_b64 exec, exec, s[4:5]
	v_mov_b32_e32 v113, 0
	s_waitcnt lgkmcnt(0)
	s_barrier
	ds_read_b32 v0, v113 offset:4
	s_mov_b32 s83, 0
	s_waitcnt lgkmcnt(0)
	v_cmp_gt_i32_e32 vcc, 0, v0
	v_readfirstlane_b32 s74, v0
	s_cbranch_vccnz .LBB0_364
	v_writelane_b32 v244, s65, 6
	v_writelane_b32 v244, s64, 7
	v_writelane_b32 v244, s75, 8
	v_writelane_b32 v244, s94, 9
	s_lshr_b32 s0, s70, 8
	s_lshl_b32 s2, s0, 6
	v_writelane_b32 v244, s95, 10
	v_writelane_b32 v244, s91, 11
	v_writelane_b32 v244, s92, 12
	s_bfe_u32 s1, s70, 0x20006
	s_lshl_b32 s34, s1, 5
	v_writelane_b32 v244, s93, 13
	v_writelane_b32 v244, s2, 14
	s_lshl_b32 s2, s71, 3
	v_writelane_b32 v244, s2, 15
	s_lshl_b32 s2, s71, 11
	s_lshl_b32 s3, s71, 10
	s_cmp_lg_u32 0, -1
	s_cselect_b32 s4, 0, 0
	v_writelane_b32 v244, s71, 16
	s_add_i32 s67, s4, s2
	s_lshl_b32 s2, s0, 13
	v_writelane_b32 v244, s2, 17
	s_add_i32 s90, s4, s3
	v_readlane_b32 s2, v244, 5
	s_add_i32 s94, s90, 0x4000
	s_add_i32 s66, s67, 0x8000
	s_add_i32 s67, s67, 0x8400
	s_addk_i32 s90, 0x6000
	s_sub_i32 s2, 0, s2
	s_lshl_b32 s1, s1, 14
	v_writelane_b32 v244, s2, 18
	s_cmp_eq_u32 s0, 1
	v_writelane_b32 v244, s1, 19
	s_cselect_b64 s[0:1], -1, 0
	v_writelane_b32 v244, s0, 20
	s_cmpk_lt_u32 s70, 0x100
	v_mov_b32_e32 v114, v113
	v_writelane_b32 v244, s1, 21
	v_writelane_b32 v244, s70, 22
	s_cselect_b64 s[0:1], -1, 0
	v_writelane_b32 v244, s0, 23
	v_mov_b32_e32 v115, v113
	v_mov_b32_e32 v112, v113
	v_writelane_b32 v244, s1, 24
	s_sub_i32 s0, s34, 64
	v_writelane_b32 v244, s0, 25
	v_writelane_b32 v244, s14, 26
	v_writelane_b32 v244, s34, 27
	v_mov_b64_e32 v[118:119], v[114:115]
	v_mov_b64_e32 v[122:123], v[114:115]
	v_mov_b64_e32 v[126:127], v[114:115]
	v_mov_b64_e32 v[130:131], v[114:115]
	v_writelane_b32 v244, s79, 28
	v_mov_b32_e32 v209, v206
	s_add_i32 s91, s14, 1
	s_mov_b64 s[4:5], -1
	s_mov_b64 s[88:89], 0x2000
	s_mov_b64 s[92:93], 0x4000
	v_mov_b32_e32 v226, 0x358637bd
	v_mov_b32_e32 v227, 0x42800000
	v_mov_b32_e32 v228, 0xff800000
	v_mov_b64_e32 v[116:117], v[112:113]
	v_mov_b64_e32 v[120:121], v[112:113]
	v_mov_b64_e32 v[124:125], v[112:113]
	v_mov_b64_e32 v[128:129], v[112:113]
	s_mov_b32 s33, 0
	s_mov_b32 s75, 0
	v_writelane_b32 v244, s56, 29
	s_nop 1
	v_writelane_b32 v244, s57, 30
	s_cmpk_lt_u32 s70, 0x100
	s_cbranch_scc1 .Lp3_noprio
	s_setprio 1
.Lp3_noprio:
	s_branch .LBB0_303
.LBB0_302:
	s_waitcnt vmcnt(0) lgkmcnt(0)

.LBB0_363:
	s_setprio 0
	v_readlane_b32 s94, v244, 9
	v_readlane_b32 s92, v244, 12
	v_readlane_b32 s91, v244, 11
	v_readlane_b32 s95, v244, 10
	v_readlane_b32 s70, v244, 22
	v_readlane_b32 s71, v244, 16
	v_readlane_b32 s75, v244, 8
	v_readlane_b32 s64, v244, 7
	v_readlane_b32 s65, v244, 6
	v_readlane_b32 s93, v244, 13
